# G1 conv: v tensor's 8 tokens per thread split between waves 4,5 (tokens 0..3) and the previously idle waves 6,7 (tokens 4..7), which now load the v rows too
# speedup vs baseline: 1.0064x; 1.0005x over previous
.Lg1_set:
	v_writelane_b32 v244, s5, 45
	v_writelane_b32 v244, s4, 46
	s_cmpk_lt_i32 s2, 0x800
	v_mbcnt_hi_u32_b32 v46, -1, v192
	v_readlane_b32 s4, v245, 0
	s_cselect_b64 s[0:1], -1, 0
	s_lshl_b64 s[10:11], s[2:3], 14
	v_add_u32_e32 v193, s4, v46
	s_cmpk_gt_i32 s2, 0x7ff
	s_nop 0
	v_readfirstlane_b32 s14, v193
	s_cbranch_scc1 .LBB0_282
	v_ashrrev_i32_e32 v44, 7, v193
	v_min_i32_e32 v44, 2, v44
	v_cmp_gt_i32_e32 vcc, 3, v44
	s_and_saveexec_b64 s[4:5], vcc
	s_cbranch_execz .LBB0_281
	v_mov_b32_e32 v0, 0xad00000
	v_mov_b32_e32 v1, 0x8d00000
	v_cmp_eq_u32_e32 vcc, 1, v44
	s_movk_i32 s13, 0x7f
	s_add_u32 s8, s92, s10
	v_cndmask_b32_e32 v0, v0, v1, vcc
	v_mov_b32_e32 v1, 0x6d00000
	v_cmp_lt_u32_e32 vcc, s13, v193
	s_addc_u32 s9, s93, s11
	s_add_i32 s12, s2, -8
	v_cndmask_b32_e32 v4, v1, v0, vcc
	v_mov_b32_e32 v5, 0
	v_ashrrev_i32_e32 v45, 31, v44
	v_lshl_add_u64 v[0:1], s[8:9], 0, v[4:5]
	v_mad_i64_i32 v[2:3], s[8:9], s12, 3, v[44:45]
	s_movk_i32 s12, 0x300
	v_mov_b64_e32 v[6:7], s[30:31]
	v_mad_u64_u32 v[6:7], s[8:9], v2, s12, v[6:7]
	s_and_b32 s6, s2, 0xf8
	v_mad_i32_i24 v7, v3, s12, v7
	v_lshrrev_b32_e32 v2, 1, v193
	v_lshlrev_b32_e32 v3, 4, v193
	s_cmp_lg_u32 s6, 0
	v_and_b32_e32 v2, 56, v2
	v_and_b32_e32 v4, 0xf0, v3
	s_cselect_b64 s[6:7], -1, 0
	v_lshl_add_u64 v[12:13], v[0:1], 0, v[4:5]
	v_cmp_ne_u32_e64 s[40:41], 0, v2
	v_lshlrev_b32_e32 v14, 8, v2
	s_and_saveexec_b64 s[8:9], s[40:41]
	s_xor_b64 s[8:9], exec, s[8:9]
	s_cbranch_execz .LBB0_264
	v_mov_b32_e32 v15, v5
	v_lshl_add_u64 v[0:1], v[12:13], 0, v[14:15]
	global_load_dwordx4 v[0:3], v[0:1], off offset:-768

.Lg1_nostr:
	s_mov_b32 s97, s2
	v_ashrrev_i32_e32 v217, 7, v193
	v_min_i32_e32 v217, 2, v217
	v_and_b32_e32 v242, 15, v193
	s_and_b32 s38, s2, 7
	s_lshl_b32 s38, s38, 9
	v_cmp_gt_i32_e32 vcc, 3, v217
	s_and_saveexec_b64 s[40:41], vcc
	v_lshlrev_b32_e32 v217, 12, v217
	v_lshl_add_u32 v217, v242, 5, v217
	v_add_u32_e32 v217, s38, v217
	global_load_dwordx4 v[218:221], v217, s[82:83]
	global_load_dwordx4 v[222:225], v217, s[82:83] offset:16
	v_add_u32_e32 v242, 0x3000, v217
	global_load_dwordx4 v[226:229], v242, s[82:83]
	global_load_dwordx4 v[230:233], v242, s[82:83] offset:16
	v_add_u32_e32 v242, 0x6000, v217
	global_load_dwordx4 v[234:237], v242, s[82:83]
	global_load_dwordx4 v[238:241], v242, s[82:83] offset:16
	v_add_u32_e32 v242, 0x9000, v217
	global_load_dwordx4 v[248:251], v242, s[82:83]
	global_load_dwordx4 v[252:255], v242, s[82:83] offset:16
	s_or_b64 exec, exec, s[40:41]
	s_waitcnt vmcnt(0)
	s_branch .LBB0_286

.LBB0_290:
	v_ashrrev_i32_e32 v188, 7, v210
	s_nop 0
	v_readfirstlane_b32 s32, v188
	v_and_b32_e32 v211, 15, v210
	v_cmp_lt_i32_e32 vcc, 3, v188
	v_cmp_gt_i32_e64 s[38:39], 4, v188
	s_and_saveexec_b64 s[44:45], s[38:39]
	s_cbranch_execz .LBB0_308
	v_mov_b64_e32 v[58:59], v[218:219]
	v_mov_b64_e32 v[60:61], v[220:221]
	v_mov_b64_e32 v[46:47], v[222:223]
	v_mov_b64_e32 v[48:49], v[224:225]
	v_mov_b64_e32 v[62:63], v[226:227]
	v_mov_b64_e32 v[64:65], v[228:229]
	v_mov_b64_e32 v[50:51], v[230:231]
	v_mov_b64_e32 v[52:53], v[232:233]
	v_mov_b64_e32 v[70:71], v[234:235]
	v_mov_b64_e32 v[72:73], v[236:237]
	v_mov_b64_e32 v[54:55], v[238:239]
	v_mov_b64_e32 v[56:57], v[240:241]
	v_mov_b64_e32 v[74:75], v[248:249]
	v_mov_b64_e32 v[76:77], v[250:251]
	v_mov_b64_e32 v[66:67], v[252:253]
	v_mov_b64_e32 v[68:69], v[254:255]
	s_cmp_eq_u32 s32, 3
	s_cbranch_scc0 .Lg1a_norm
	s_waitcnt vmcnt(0)
	v_lshlrev_b32_e32 v110, 16, v19
	v_and_b32_e32 v111, 0xffff0000, v19
	v_lshlrev_b32_e32 v112, 16, v23
	v_and_b32_e32 v113, 0xffff0000, v23
	v_lshlrev_b32_e32 v118, 16, v18
	v_and_b32_e32 v119, 0xffff0000, v18
	v_lshlrev_b32_e32 v120, 16, v22
	v_and_b32_e32 v121, 0xffff0000, v22
	v_lshlrev_b32_e32 v122, 16, v27
	v_and_b32_e32 v123, 0xffff0000, v27
	v_lshlrev_b32_e32 v124, 16, v17
	v_and_b32_e32 v125, 0xffff0000, v17
	v_lshlrev_b32_e32 v130, 16, v21
	v_and_b32_e32 v131, 0xffff0000, v21
	v_lshlrev_b32_e32 v132, 16, v26
	v_and_b32_e32 v133, 0xffff0000, v26
	v_lshlrev_b32_e32 v134, 16, v25
	v_and_b32_e32 v135, 0xffff0000, v25
	v_lshlrev_b32_e32 v136, 16, v24
	v_and_b32_e32 v137, 0xffff0000, v24
	v_lshlrev_b32_e32 v138, 16, v16
	v_and_b32_e32 v139, 0xffff0000, v16
	v_lshlrev_b32_e32 v140, 16, v20
	v_and_b32_e32 v141, 0xffff0000, v20
	s_mov_b64 s[40:41], 0
	s_branch .Lg1a_t4
.Lg1a_norm:
	s_waitcnt vmcnt(11)
	v_lshlrev_b32_e32 v78, 16, v0
	v_and_b32_e32 v79, 0xffff0000, v0
	v_lshlrev_b32_e32 v102, 16, v4
	v_and_b32_e32 v103, 0xffff0000, v4
	v_lshlrev_b32_e32 v90, 16, v8
	v_and_b32_e32 v91, 0xffff0000, v8
	v_lshlrev_b32_e32 v100, 16, v12
	v_and_b32_e32 v101, 0xffff0000, v12
	v_lshlrev_b32_e32 v104, 16, v5
	v_and_b32_e32 v105, 0xffff0000, v5
	v_lshlrev_b32_e32 v86, 16, v9
	v_and_b32_e32 v87, 0xffff0000, v9
	v_lshlrev_b32_e32 v98, 16, v13
	v_and_b32_e32 v99, 0xffff0000, v13
	v_lshlrev_b32_e32 v106, 16, v6
	v_and_b32_e32 v107, 0xffff0000, v6
	v_lshlrev_b32_e32 v88, 16, v10
	v_and_b32_e32 v89, 0xffff0000, v10
	v_lshlrev_b32_e32 v96, 16, v14
	v_and_b32_e32 v97, 0xffff0000, v14
	v_lshlrev_b32_e32 v108, 16, v7
	v_and_b32_e32 v109, 0xffff0000, v7
	v_lshlrev_b32_e32 v92, 16, v11
	v_and_b32_e32 v93, 0xffff0000, v11
	v_lshlrev_b32_e32 v94, 16, v15
	v_and_b32_e32 v95, 0xffff0000, v15
	s_movk_i32 s8, 0x80
	v_cmp_gt_u32_e64 s[42:43], s8, v210
	v_cmp_ne_u32_e64 s[40:41], 2, v188
	v_pk_fma_f32 v[78:79], v[58:59], v[78:79], 0 op_sel_hi:[1,1,0]
	v_cndmask_b32_e64 v44, 1.0, v205, s[42:43]
	v_pk_fma_f32 v[78:79], v[62:63], v[102:103], v[78:79]
	s_nop 0
	v_pk_fma_f32 v[78:79], v[70:71], v[90:91], v[78:79]
	s_nop 0
	v_pk_fma_f32 v[78:79], v[74:75], v[100:101], v[78:79]
	s_nop 0
	v_mul_f32_e32 v80, 0xbfb8aa3b, v78
	v_mul_f32_e32 v81, 0xbfb8aa3b, v79
	v_exp_f32_e32 v80, v80
	v_exp_f32_e32 v81, v81
	v_add_f32_e32 v80, 1.0, v80
	v_add_f32_e32 v81, 1.0, v81
	v_rcp_f32_e32 v80, v80
	v_rcp_f32_e32 v81, v81
	s_nop 0
	v_pk_mul_f32 v[78:79], v[78:79], v[80:81]
	v_lshlrev_b32_e32 v80, 16, v1
	v_and_b32_e32 v81, 0xffff0000, v1
	v_pk_fma_f32 v[80:81], v[60:61], v[80:81], 0 op_sel_hi:[1,1,0]
	s_nop 0
	v_pk_fma_f32 v[80:81], v[64:65], v[104:105], v[80:81]
	s_nop 0
	v_pk_fma_f32 v[80:81], v[72:73], v[86:87], v[80:81]
	s_nop 0
	v_pk_fma_f32 v[80:81], v[76:77], v[98:99], v[80:81]
	s_nop 0
	v_mul_f32_e32 v82, 0xbfb8aa3b, v80
	v_mul_f32_e32 v83, 0xbfb8aa3b, v81
	v_exp_f32_e32 v82, v82
	v_exp_f32_e32 v83, v83
	v_add_f32_e32 v82, 1.0, v82
	v_add_f32_e32 v83, 1.0, v83
	v_rcp_f32_e32 v82, v82
	v_rcp_f32_e32 v83, v83
	s_nop 0
	v_pk_mul_f32 v[80:81], v[80:81], v[82:83]
	v_lshlrev_b32_e32 v82, 16, v2
	v_and_b32_e32 v83, 0xffff0000, v2
	v_pk_fma_f32 v[82:83], v[46:47], v[82:83], 0 op_sel_hi:[1,1,0]
	s_nop 0
	v_pk_fma_f32 v[82:83], v[50:51], v[106:107], v[82:83]
	s_nop 0
	v_pk_fma_f32 v[82:83], v[54:55], v[88:89], v[82:83]
	s_nop 0
	v_pk_fma_f32 v[82:83], v[66:67], v[96:97], v[82:83]
	s_nop 0
	v_mul_f32_e32 v84, 0xbfb8aa3b, v82
	v_mul_f32_e32 v85, 0xbfb8aa3b, v83
	v_exp_f32_e32 v84, v84
	v_exp_f32_e32 v85, v85
	v_add_f32_e32 v84, 1.0, v84
	v_add_f32_e32 v85, 1.0, v85
	v_rcp_f32_e32 v84, v84
	v_rcp_f32_e32 v85, v85
	s_nop 0
	v_pk_mul_f32 v[82:83], v[82:83], v[84:85]
	v_lshlrev_b32_e32 v84, 16, v3
	v_and_b32_e32 v85, 0xffff0000, v3
	v_pk_fma_f32 v[84:85], v[48:49], v[84:85], 0 op_sel_hi:[1,1,0]
	s_nop 0
	v_pk_fma_f32 v[84:85], v[52:53], v[108:109], v[84:85]
	s_nop 0
	v_pk_fma_f32 v[84:85], v[56:57], v[92:93], v[84:85]
	s_nop 0
	v_pk_fma_f32 v[84:85], v[68:69], v[94:95], v[84:85]
	s_nop 0
	v_mul_f32_e32 v110, 0xbfb8aa3b, v84
	v_mul_f32_e32 v111, 0xbfb8aa3b, v85
	v_exp_f32_e32 v110, v110
	v_exp_f32_e32 v111, v111
	v_add_f32_e32 v110, 1.0, v110
	v_add_f32_e32 v111, 1.0, v111
	v_rcp_f32_e32 v110, v110
	v_rcp_f32_e32 v111, v111
	s_nop 0
	v_pk_mul_f32 v[84:85], v[84:85], v[110:111]
	s_and_saveexec_b64 s[8:9], s[40:41]
	s_cbranch_execz .LBB0_293
	v_pk_mul_f32 v[110:111], v[78:79], v[78:79]
	v_pk_mul_f32 v[112:113], v[80:81], v[80:81]
	v_add_f32_e32 v110, v110, v111
	v_add_f32_e32 v110, v112, v110
	v_pk_mul_f32 v[114:115], v[82:83], v[82:83]
	v_add_f32_e32 v110, v113, v110
	v_add_f32_e32 v110, v114, v110
	v_pk_mul_f32 v[116:117], v[84:85], v[84:85]
	v_add_f32_e32 v110, v115, v110
	v_add_f32_e32 v110, v116, v110
	v_add_f32_e32 v110, v117, v110
	ds_bpermute_b32 v111, v201, v110
	s_waitcnt lgkmcnt(0)
	v_add_f32_e32 v110, v110, v111
	ds_bpermute_b32 v111, v202, v110
	s_waitcnt lgkmcnt(0)
	v_add_f32_e32 v110, v110, v111
	ds_bpermute_b32 v111, v203, v110
	s_waitcnt lgkmcnt(0)
	v_add_f32_e32 v110, v110, v111
	ds_bpermute_b32 v111, v204, v110
	s_waitcnt lgkmcnt(0)
	v_add_f32_e32 v110, v110, v111
	v_add_f32_e32 v110, 0x358637bd, v110
	v_rsq_f32_e32 v110, v110
	s_nop 0
	v_mul_f32_e32 v110, v44, v110
	v_pk_mul_f32 v[78:79], v[78:79], v[110:111] op_sel_hi:[1,0]
	v_pk_mul_f32 v[80:81], v[80:81], v[110:111] op_sel_hi:[1,0]
	v_pk_mul_f32 v[82:83], v[82:83], v[110:111] op_sel_hi:[1,0]
	v_pk_mul_f32 v[84:85], v[84:85], v[110:111] op_sel_hi:[1,0]

.LBB0_299:
	s_or_b64 exec, exec, s[8:9]
	s_cmp_eq_u32 s32, 2
	s_cbranch_scc1 .LBB0_308
.Lg1a_t4:
	v_pk_fma_f32 v[94:95], v[58:59], v[138:139], 0 op_sel_hi:[1,1,0]
	v_lshlrev_b32_e32 v152, 16, v28
	v_and_b32_e32 v150, 0xffff0000, v28
	v_pk_fma_f32 v[94:95], v[62:63], v[140:141], v[94:95]
	v_mov_b32_e32 v156, v152
	v_pk_fma_f32 v[94:95], v[70:71], v[136:137], v[94:95]
	v_mov_b32_e32 v157, v150
	v_pk_fma_f32 v[94:95], v[74:75], v[156:157], v[94:95]
	v_lshlrev_b32_e32 v148, 16, v29
	v_mul_f32_e32 v96, 0xbfb8aa3b, v94
	v_mul_f32_e32 v97, 0xbfb8aa3b, v95
	v_exp_f32_e32 v96, v96
	v_exp_f32_e32 v97, v97
	v_and_b32_e32 v146, 0xffff0000, v29
	v_mov_b32_e32 v158, v148
	v_add_f32_e32 v96, 1.0, v96
	v_add_f32_e32 v97, 1.0, v97
	v_rcp_f32_e32 v96, v96
	v_rcp_f32_e32 v97, v97
	v_mov_b32_e32 v159, v146
	v_and_b32_e32 v145, 0xffff0000, v30
	v_lshlrev_b32_e32 v144, 16, v30
	v_pk_mul_f32 v[96:97], v[94:95], v[96:97]
	v_pk_fma_f32 v[94:95], v[60:61], v[124:125], 0 op_sel_hi:[1,1,0]
	v_and_b32_e32 v143, 0xffff0000, v31
	v_pk_fma_f32 v[94:95], v[64:65], v[130:131], v[94:95]
	v_lshlrev_b32_e32 v142, 16, v31
	v_pk_fma_f32 v[94:95], v[72:73], v[134:135], v[94:95]
	v_lshlrev_b32_e32 v153, 16, v32
	v_pk_fma_f32 v[94:95], v[76:77], v[158:159], v[94:95]
	v_and_b32_e32 v151, 0xffff0000, v32
	v_mul_f32_e32 v98, 0xbfb8aa3b, v94
	v_mul_f32_e32 v99, 0xbfb8aa3b, v95
	v_exp_f32_e32 v98, v98
	v_exp_f32_e32 v99, v99
	v_lshlrev_b32_e32 v149, 16, v33
	v_and_b32_e32 v147, 0xffff0000, v33
	v_add_f32_e32 v98, 1.0, v98
	v_add_f32_e32 v99, 1.0, v99
	v_rcp_f32_e32 v98, v98
	v_rcp_f32_e32 v99, v99
	s_nop 0
	v_pk_mul_f32 v[94:95], v[94:95], v[98:99]
	v_pk_fma_f32 v[98:99], v[46:47], v[118:119], 0 op_sel_hi:[1,1,0]
	s_nop 0
	v_pk_fma_f32 v[98:99], v[50:51], v[120:121], v[98:99]
	s_nop 0
	v_pk_fma_f32 v[98:99], v[54:55], v[132:133], v[98:99]
	s_nop 0
	v_pk_fma_f32 v[98:99], v[66:67], v[144:145], v[98:99]
	s_nop 0
	v_mul_f32_e32 v100, 0xbfb8aa3b, v98
	v_mul_f32_e32 v101, 0xbfb8aa3b, v99
	v_exp_f32_e32 v100, v100
	v_exp_f32_e32 v101, v101
	v_add_f32_e32 v100, 1.0, v100
	v_add_f32_e32 v101, 1.0, v101
	v_rcp_f32_e32 v100, v100
	v_rcp_f32_e32 v101, v101
	s_nop 0
	v_pk_mul_f32 v[98:99], v[98:99], v[100:101]
	v_pk_fma_f32 v[100:101], v[48:49], v[110:111], 0 op_sel_hi:[1,1,0]
	s_nop 0
	v_pk_fma_f32 v[100:101], v[52:53], v[112:113], v[100:101]
	s_nop 0
	v_pk_fma_f32 v[100:101], v[56:57], v[122:123], v[100:101]
	s_nop 0
	v_pk_fma_f32 v[100:101], v[68:69], v[142:143], v[100:101]
	s_nop 0
	v_mul_f32_e32 v110, 0xbfb8aa3b, v100
	v_mul_f32_e32 v111, 0xbfb8aa3b, v101
	v_exp_f32_e32 v110, v110
	v_exp_f32_e32 v111, v111
	v_add_f32_e32 v110, 1.0, v110
	v_add_f32_e32 v111, 1.0, v111
	v_rcp_f32_e32 v110, v110
	v_rcp_f32_e32 v111, v111
	s_nop 0
	v_pk_mul_f32 v[100:101], v[100:101], v[110:111]
	s_and_saveexec_b64 s[8:9], s[40:41]
	s_cbranch_execz .LBB0_301
	v_pk_mul_f32 v[110:111], v[96:97], v[96:97]
	v_pk_mul_f32 v[118:119], v[94:95], v[94:95]
	v_add_f32_e32 v110, v110, v111
	v_add_f32_e32 v110, v118, v110
	v_pk_mul_f32 v[124:125], v[98:99], v[98:99]
	v_add_f32_e32 v110, v119, v110
	v_add_f32_e32 v110, v124, v110
	v_pk_mul_f32 v[138:139], v[100:101], v[100:101]
	v_add_f32_e32 v110, v125, v110
	v_add_f32_e32 v110, v138, v110
	v_add_f32_e32 v110, v139, v110
	ds_bpermute_b32 v111, v201, v110
	s_waitcnt lgkmcnt(0)
	v_add_f32_e32 v110, v110, v111
	ds_bpermute_b32 v111, v202, v110
	s_waitcnt lgkmcnt(0)
	v_add_f32_e32 v110, v110, v111
	ds_bpermute_b32 v111, v203, v110
	s_waitcnt lgkmcnt(0)
	v_add_f32_e32 v110, v110, v111
	ds_bpermute_b32 v111, v204, v110
	s_waitcnt lgkmcnt(0)
	v_add_f32_e32 v110, v110, v111
	v_add_f32_e32 v110, 0x358637bd, v110
	v_rsq_f32_e32 v110, v110
	s_nop 0
	v_mul_f32_e32 v110, v44, v110
	v_pk_mul_f32 v[96:97], v[96:97], v[110:111] op_sel_hi:[1,0]
	v_pk_mul_f32 v[94:95], v[94:95], v[110:111] op_sel_hi:[1,0]
	v_pk_mul_f32 v[98:99], v[98:99], v[110:111] op_sel_hi:[1,0]
	v_pk_mul_f32 v[100:101], v[100:101], v[110:111] op_sel_hi:[1,0]

.LBB0_308:
	s_or_b64 exec, exec, s[44:45]
	v_lshrrev_b32_e32 v212, 4, v210
	s_waitcnt vmcnt(0) lgkmcnt(0)
	s_barrier
	s_and_saveexec_b64 s[8:9], s[38:39]
	s_cbranch_execz .LBB0_359
	v_readfirstlane_b32 s38, v188
	v_and_b32_e32 v44, 7, v212
	v_lshlrev_b32_e32 v70, 5, v44
	v_add_u32_e32 v70, 0x1f500, v70
	s_cmp_eq_u32 s38, 1
	s_cbranch_scc1 .Lg1b_k
	s_cmp_ge_u32 s38, 2
	s_cbranch_scc1 .Lg1b_v
	ds_read_b128 v[58:61], v70
	ds_read_b128 v[62:65], v70 offset:16
	v_and_b32_e32 v72, 3, v211
	v_lshrrev_b32_e32 v74, 2, v211
	v_lshlrev_b32_e32 v146, 1, v72
	v_and_b32_e32 v147, 1, v74
	v_xor_b32_e32 v146, v146, v147
	v_lshrrev_b32_e32 v76, 1, v44
	v_lshl_add_u32 v76, v76, 2, v74
	v_lshlrev_b32_e32 v76, 6, v76
	v_lshl_add_u32 v76, v72, 4, v76
	v_and_b32_e32 v147, 1, v44
	v_lshl_add_u32 v76, v147, 3, v76
	v_lshlrev_b32_e32 v76, 4, v76
	v_lshl_add_u32 v76, v146, 4, v76
	v_cvt_pk_bf16_f32 v50, v78, v79
	v_cvt_pk_bf16_f32 v51, v80, v81
	v_cvt_pk_bf16_f32 v52, v82, v83
	v_cvt_pk_bf16_f32 v53, v84, v85
	ds_write_b128 v76, v[50:53]
	v_cvt_pk_bf16_f32 v54, v102, v103
	v_cvt_pk_bf16_f32 v55, v104, v105
	v_cvt_pk_bf16_f32 v56, v106, v107
	v_cvt_pk_bf16_f32 v57, v108, v109
	v_xor_b32_e32 v147, 0x10, v76
	ds_write_b128 v147, v[54:57]
	v_cvt_pk_bf16_f32 v50, v90, v91
	v_cvt_pk_bf16_f32 v51, v86, v87
	v_cvt_pk_bf16_f32 v52, v88, v89
	v_cvt_pk_bf16_f32 v53, v92, v93
	v_xor_b32_e32 v146, 0x20, v76
	ds_write_b128 v146, v[50:53]
	v_cvt_pk_bf16_f32 v54, v114, v115
	v_cvt_pk_bf16_f32 v55, v116, v117
	v_cvt_pk_bf16_f32 v56, v126, v127
	v_cvt_pk_bf16_f32 v57, v128, v129
	v_xor_b32_e32 v147, 0x30, v76
	ds_write_b128 v147, v[54:57]
	v_cvt_pk_bf16_f32 v50, v96, v97
	v_cvt_pk_bf16_f32 v51, v94, v95
	v_cvt_pk_bf16_f32 v52, v98, v99
	v_cvt_pk_bf16_f32 v53, v100, v101
	v_xor_b32_e32 v146, 0x40, v76
	ds_write_b128 v146, v[50:53]
	v_cvt_pk_bf16_f32 v54, v138, v139
	v_cvt_pk_bf16_f32 v55, v140, v141
	v_cvt_pk_bf16_f32 v56, v154, v155
	v_cvt_pk_bf16_f32 v57, v130, v131
	v_xor_b32_e32 v147, 0x50, v76
	ds_write_b128 v147, v[54:57]
	v_cvt_pk_bf16_f32 v50, v156, v157
	v_cvt_pk_bf16_f32 v51, v136, v137
	v_cvt_pk_bf16_f32 v52, v112, v113
	v_cvt_pk_bf16_f32 v53, v110, v111
	v_xor_b32_e32 v146, 0x60, v76
	ds_write_b128 v146, v[50:53]
	v_cvt_pk_bf16_f32 v54, v71, v75
	v_cvt_pk_bf16_f32 v55, v77, v73
	v_cvt_pk_bf16_f32 v56, v46, v47
	v_cvt_pk_bf16_f32 v57, v48, v49
	v_xor_b32_e32 v147, 0x70, v76
	ds_write_b128 v147, v[54:57]
	v_mul_u32_u24_e32 v72, 0x880, v44
	v_lshl_add_u32 v72, v211, 4, v72
	v_add_u32_e32 v72, 0x10400, v72
	s_waitcnt lgkmcnt(8)
	v_pk_mul_f32 v[66:67], v[78:79], v[58:59] op_sel_hi:[1,0]
	v_pk_mul_f32 v[68:69], v[80:81], v[58:59] op_sel_hi:[1,0]
	v_pk_mul_f32 v[142:143], v[82:83], v[58:59] op_sel_hi:[1,0]
	v_pk_mul_f32 v[144:145], v[84:85], v[58:59] op_sel_hi:[1,0]
	v_cvt_pk_bf16_f32 v50, v66, v67
	v_cvt_pk_bf16_f32 v51, v68, v69
	v_cvt_pk_bf16_f32 v52, v142, v143
	v_cvt_pk_bf16_f32 v53, v144, v145
	ds_write_b128 v72, v[50:53]
	v_pk_mul_f32 v[66:67], v[102:103], v[58:59] op_sel:[0,1]
	v_pk_mul_f32 v[68:69], v[104:105], v[58:59] op_sel:[0,1]
	v_pk_mul_f32 v[142:143], v[106:107], v[58:59] op_sel:[0,1]
	v_pk_mul_f32 v[144:145], v[108:109], v[58:59] op_sel:[0,1]
	v_cvt_pk_bf16_f32 v54, v66, v67
	v_cvt_pk_bf16_f32 v55, v68, v69
	v_cvt_pk_bf16_f32 v56, v142, v143
	v_cvt_pk_bf16_f32 v57, v144, v145
	ds_write_b128 v72, v[54:57] offset:272
	v_pk_mul_f32 v[66:67], v[90:91], v[60:61] op_sel_hi:[1,0]
	v_pk_mul_f32 v[68:69], v[86:87], v[60:61] op_sel_hi:[1,0]
	v_pk_mul_f32 v[142:143], v[88:89], v[60:61] op_sel_hi:[1,0]
	v_pk_mul_f32 v[144:145], v[92:93], v[60:61] op_sel_hi:[1,0]
	v_cvt_pk_bf16_f32 v50, v66, v67
	v_cvt_pk_bf16_f32 v51, v68, v69
	v_cvt_pk_bf16_f32 v52, v142, v143
	v_cvt_pk_bf16_f32 v53, v144, v145
	ds_write_b128 v72, v[50:53] offset:544
	v_pk_mul_f32 v[66:67], v[114:115], v[60:61] op_sel:[0,1]
	v_pk_mul_f32 v[68:69], v[116:117], v[60:61] op_sel:[0,1]
	v_pk_mul_f32 v[142:143], v[126:127], v[60:61] op_sel:[0,1]
	v_pk_mul_f32 v[144:145], v[128:129], v[60:61] op_sel:[0,1]
	v_cvt_pk_bf16_f32 v54, v66, v67
	v_cvt_pk_bf16_f32 v55, v68, v69
	v_cvt_pk_bf16_f32 v56, v142, v143
	v_cvt_pk_bf16_f32 v57, v144, v145
	ds_write_b128 v72, v[54:57] offset:816
	v_pk_mul_f32 v[66:67], v[96:97], v[62:63] op_sel_hi:[1,0]
	v_pk_mul_f32 v[68:69], v[94:95], v[62:63] op_sel_hi:[1,0]
	v_pk_mul_f32 v[142:143], v[98:99], v[62:63] op_sel_hi:[1,0]
	v_pk_mul_f32 v[144:145], v[100:101], v[62:63] op_sel_hi:[1,0]
	v_cvt_pk_bf16_f32 v50, v66, v67
	v_cvt_pk_bf16_f32 v51, v68, v69
	v_cvt_pk_bf16_f32 v52, v142, v143
	v_cvt_pk_bf16_f32 v53, v144, v145
	ds_write_b128 v72, v[50:53] offset:1088
	v_pk_mul_f32 v[66:67], v[138:139], v[62:63] op_sel:[0,1]
	v_pk_mul_f32 v[68:69], v[140:141], v[62:63] op_sel:[0,1]
	v_pk_mul_f32 v[142:143], v[154:155], v[62:63] op_sel:[0,1]
	v_pk_mul_f32 v[144:145], v[130:131], v[62:63] op_sel:[0,1]
	v_cvt_pk_bf16_f32 v54, v66, v67
	v_cvt_pk_bf16_f32 v55, v68, v69
	v_cvt_pk_bf16_f32 v56, v142, v143
	v_cvt_pk_bf16_f32 v57, v144, v145
	ds_write_b128 v72, v[54:57] offset:1360
	v_pk_mul_f32 v[66:67], v[156:157], v[64:65] op_sel_hi:[1,0]
	v_pk_mul_f32 v[68:69], v[136:137], v[64:65] op_sel_hi:[1,0]
	v_pk_mul_f32 v[142:143], v[112:113], v[64:65] op_sel_hi:[1,0]
	v_pk_mul_f32 v[144:145], v[110:111], v[64:65] op_sel_hi:[1,0]
	v_cvt_pk_bf16_f32 v50, v66, v67
	v_cvt_pk_bf16_f32 v51, v68, v69
	v_cvt_pk_bf16_f32 v52, v142, v143
	v_cvt_pk_bf16_f32 v53, v144, v145
	ds_write_b128 v72, v[50:53] offset:1632
	v_mul_f32_e32 v66, v71, v65
	v_mul_f32_e32 v67, v75, v65
	v_mul_f32_e32 v68, v77, v65
	v_mul_f32_e32 v69, v73, v65
	v_pk_mul_f32 v[142:143], v[46:47], v[64:65] op_sel:[0,1]
	v_pk_mul_f32 v[144:145], v[48:49], v[64:65] op_sel:[0,1]
	v_cvt_pk_bf16_f32 v54, v66, v67
	v_cvt_pk_bf16_f32 v55, v68, v69
	v_cvt_pk_bf16_f32 v56, v142, v143
	v_cvt_pk_bf16_f32 v57, v144, v145
	ds_write_b128 v72, v[54:57] offset:1904
	s_branch .LBB0_359
.Lg1b_v:
	ds_read_b128 v[50:53], v70 offset:256
	ds_read_b128 v[54:57], v70 offset:272
	v_mul_u32_u24_e32 v72, 0x1080, v44
	v_lshl_add_u32 v72, v211, 4, v72
	v_add_u32_e32 v72, 0x8000, v72
	s_waitcnt lgkmcnt(0)
	s_cmp_eq_u32 s32, 3
	s_cbranch_scc1 .Lg1b_v67
	v_pk_mul_f32 v[66:67], v[78:79], v[50:51] op_sel_hi:[1,0]
	v_pk_mul_f32 v[68:69], v[80:81], v[50:51] op_sel_hi:[1,0]
	v_pk_mul_f32 v[142:143], v[82:83], v[50:51] op_sel_hi:[1,0]
	v_pk_mul_f32 v[144:145], v[84:85], v[50:51] op_sel_hi:[1,0]
	v_cvt_pk_bf16_f32 v58, v66, v67
	v_cvt_pk_bf16_f32 v59, v68, v69
	v_cvt_pk_bf16_f32 v60, v142, v143
	v_cvt_pk_bf16_f32 v61, v144, v145
	ds_write_b128 v72, v[58:61]
	v_pk_mul_f32 v[66:67], v[102:103], v[50:51] op_sel:[0,1]
	v_pk_mul_f32 v[68:69], v[104:105], v[50:51] op_sel:[0,1]
	v_pk_mul_f32 v[142:143], v[106:107], v[50:51] op_sel:[0,1]
	v_pk_mul_f32 v[144:145], v[108:109], v[50:51] op_sel:[0,1]
	v_cvt_pk_bf16_f32 v62, v66, v67
	v_cvt_pk_bf16_f32 v63, v68, v69
	v_cvt_pk_bf16_f32 v64, v142, v143
	v_cvt_pk_bf16_f32 v65, v144, v145
	ds_write_b128 v72, v[62:65] offset:528
	v_pk_mul_f32 v[66:67], v[90:91], v[52:53] op_sel_hi:[1,0]
	v_pk_mul_f32 v[68:69], v[86:87], v[52:53] op_sel_hi:[1,0]
	v_pk_mul_f32 v[142:143], v[88:89], v[52:53] op_sel_hi:[1,0]
	v_pk_mul_f32 v[144:145], v[92:93], v[52:53] op_sel_hi:[1,0]
	v_cvt_pk_bf16_f32 v58, v66, v67
	v_cvt_pk_bf16_f32 v59, v68, v69
	v_cvt_pk_bf16_f32 v60, v142, v143
	v_cvt_pk_bf16_f32 v61, v144, v145
	ds_write_b128 v72, v[58:61] offset:1056
	v_pk_mul_f32 v[66:67], v[114:115], v[52:53] op_sel:[0,1]
	v_pk_mul_f32 v[68:69], v[116:117], v[52:53] op_sel:[0,1]
	v_pk_mul_f32 v[142:143], v[126:127], v[52:53] op_sel:[0,1]
	v_pk_mul_f32 v[144:145], v[128:129], v[52:53] op_sel:[0,1]
	v_cvt_pk_bf16_f32 v62, v66, v67
	v_cvt_pk_bf16_f32 v63, v68, v69
	v_cvt_pk_bf16_f32 v64, v142, v143
	v_cvt_pk_bf16_f32 v65, v144, v145
	ds_write_b128 v72, v[62:65] offset:1584
	s_branch .LBB0_359
.Lg1b_v67:
	v_pk_mul_f32 v[66:67], v[96:97], v[54:55] op_sel_hi:[1,0]
	v_pk_mul_f32 v[68:69], v[94:95], v[54:55] op_sel_hi:[1,0]
	v_pk_mul_f32 v[142:143], v[98:99], v[54:55] op_sel_hi:[1,0]
	v_pk_mul_f32 v[144:145], v[100:101], v[54:55] op_sel_hi:[1,0]
	v_cvt_pk_bf16_f32 v58, v66, v67
	v_cvt_pk_bf16_f32 v59, v68, v69
	v_cvt_pk_bf16_f32 v60, v142, v143
	v_cvt_pk_bf16_f32 v61, v144, v145
	ds_write_b128 v72, v[58:61] offset:2112
	v_pk_mul_f32 v[66:67], v[138:139], v[54:55] op_sel:[0,1]
	v_pk_mul_f32 v[68:69], v[140:141], v[54:55] op_sel:[0,1]
	v_pk_mul_f32 v[142:143], v[154:155], v[54:55] op_sel:[0,1]
	v_pk_mul_f32 v[144:145], v[130:131], v[54:55] op_sel:[0,1]
	v_cvt_pk_bf16_f32 v62, v66, v67
	v_cvt_pk_bf16_f32 v63, v68, v69
	v_cvt_pk_bf16_f32 v64, v142, v143
	v_cvt_pk_bf16_f32 v65, v144, v145
	ds_write_b128 v72, v[62:65] offset:2640
	v_pk_mul_f32 v[66:67], v[156:157], v[56:57] op_sel_hi:[1,0]
	v_pk_mul_f32 v[68:69], v[136:137], v[56:57] op_sel_hi:[1,0]
	v_pk_mul_f32 v[142:143], v[112:113], v[56:57] op_sel_hi:[1,0]
	v_pk_mul_f32 v[144:145], v[110:111], v[56:57] op_sel_hi:[1,0]
	v_cvt_pk_bf16_f32 v58, v66, v67
	v_cvt_pk_bf16_f32 v59, v68, v69
	v_cvt_pk_bf16_f32 v60, v142, v143
	v_cvt_pk_bf16_f32 v61, v144, v145
	ds_write_b128 v72, v[58:61] offset:3168
	v_mul_f32_e32 v66, v71, v57
	v_mul_f32_e32 v67, v75, v57
	v_mul_f32_e32 v68, v77, v57
	v_mul_f32_e32 v69, v73, v57
	v_pk_mul_f32 v[142:143], v[46:47], v[56:57] op_sel:[0,1]
	v_pk_mul_f32 v[144:145], v[48:49], v[56:57] op_sel:[0,1]
	v_cvt_pk_bf16_f32 v62, v66, v67
	v_cvt_pk_bf16_f32 v63, v68, v69
	v_cvt_pk_bf16_f32 v64, v142, v143
	v_cvt_pk_bf16_f32 v65, v144, v145
	ds_write_b128 v72, v[62:65] offset:3696
	s_branch .LBB0_359
